# rwkv_prep first token group: three previous-token row loads issued together
# speedup vs baseline: 1.0057x; 1.0057x over previous
.LBB0_663:
	s_or_b64 exec, exec, s[6:7]
	v_and_b32_e32 v1, 15, v82
	v_cndmask_b32_e64 v3, v245, v246, s[4:5]
	v_and_b32_e32 v64, 0xffffffcf, v82
	v_add3_u32 v5, v8, v7, v3
	v_cvt_pk_bf16_f32 v2, v6, v2
	v_cvt_pk_bf16_f32 v3, v4, v0
	v_and_b32_e32 v144, 48, v82
	v_mul_u32_u24_e32 v0, 0x48, v1
	v_ashrrev_i32_e32 v65, 31, v64
	v_lshl_add_u64 v[48:49], s[12:13], 0, v[144:145]
	v_lshl_add_u64 v[50:51], s[14:15], 0, v[144:145]
	v_lshlrev_b32_e32 v0, 1, v0
	v_lshlrev_b64 v[20:21], 7, v[64:65]
	v_add3_u32 v73, 0, v144, v0
	v_lshl_add_u64 v[52:53], v[48:49], 0, v[20:21]
	v_lshl_add_u64 v[54:55], v[50:51], 0, v[20:21]
	s_mov_b64 s[34:35], 0x1000
	v_lshl_add_u64 v[130:131], v[52:53], 0, s[34:35]
	v_lshl_add_u64 v[132:133], v[54:55], 0, s[34:35]
	global_load_dwordx4 v[162:165], v[52:53], off
	global_load_dwordx4 v[166:169], v[54:55], off
	global_load_dwordx4 v[170:173], v[52:53], off offset:2048
	global_load_dwordx4 v[174:177], v[54:55], off offset:2048
	global_load_dwordx4 v[178:181], v[130:131], off
	global_load_dwordx4 v[182:185], v[132:133], off
	global_load_dwordx4 v[186:189], v[130:131], off offset:2048
	global_load_dwordx4 v[190:193], v[132:133], off offset:2048
	global_load_dwordx4 v[194:197], v[52:53], off offset:64
	global_load_dwordx4 v[198:201], v[54:55], off offset:64
	global_load_dwordx4 v[202:205], v[52:53], off offset:2112
	global_load_dwordx4 v[206:209], v[54:55], off offset:2112
	global_load_dwordx4 v[210:213], v[130:131], off offset:64
	global_load_dwordx4 v[214:217], v[132:133], off offset:64
	global_load_dwordx4 v[218:221], v[130:131], off offset:2112
	global_load_dwordx4 v[222:225], v[132:133], off offset:2112
	ds_write_b64 v5, v[2:3]
	s_waitcnt lgkmcnt(0)
	s_barrier
	ds_read_b128 v[0:3], v73
	ds_read_b128 v[4:7], v73 offset:4608
	ds_read_b128 v[8:11], v73 offset:2304
	ds_read_b128 v[12:15], v73 offset:6912
	v_or_b32_e32 v68, 16, v64
	v_ashrrev_i32_e32 v69, 31, v68
	v_lshlrev_b64 v[36:37], 7, v[68:69]
	v_lshl_add_u64 v[74:75], v[48:49], 0, v[36:37]
	v_lshl_add_u64 v[128:129], v[50:51], 0, v[36:37]
	v_or_b32_e32 v66, 32, v64
	v_ashrrev_i32_e32 v67, 31, v66
	v_or_b32_e32 v70, 48, v82
	v_ashrrev_i32_e32 v71, 31, v70
	v_bfe_u32 v72, v82, 4, 2
	v_mul_u32_u24_e32 v65, 0x810, v72
	v_and_b32_e32 v77, 63, v82
	v_ashrrev_i32_e32 v83, 6, v82
	v_add_u32_e32 v76, s36, v83
	v_lshlrev_b32_e32 v144, 4, v77
	s_waitcnt vmcnt(0) lgkmcnt(2)
	v_mfma_f32_16x16x32_bf16 v[28:31], v[4:7], v[166:169], 0
	s_waitcnt lgkmcnt(0)
	v_mfma_f32_16x16x32_bf16 v[32:35], v[12:15], v[166:169], 0
	v_mfma_f32_16x16x32_bf16 v[24:27], v[0:3], v[162:165], 0
	v_mfma_f32_16x16x32_bf16 v[16:19], v[8:11], v[162:165], 0
	v_mfma_f32_16x16x32_bf16 v[44:47], v[4:7], v[174:177], 0
	v_mfma_f32_16x16x32_bf16 v[60:63], v[12:15], v[174:177], 0
	v_lshlrev_b64 v[36:37], 7, v[66:67]
	v_lshl_add_u64 v[130:131], v[48:49], 0, v[36:37]
	v_lshl_add_u64 v[132:133], v[50:51], 0, v[36:37]
	v_mfma_f32_16x16x32_bf16 v[40:43], v[0:3], v[170:173], 0
	v_add_lshl_u32 v67, v65, v64, 2
	v_add_u32_e32 v69, 0, v67
	v_mfma_f32_16x16x32_bf16 v[56:59], v[8:11], v[170:173], 0
	v_mfma_f32_16x16x32_bf16 v[84:87], v[4:7], v[182:185], 0
	v_mfma_f32_16x16x32_bf16 v[92:95], v[12:15], v[182:185], 0
	v_lshlrev_b64 v[36:37], 7, v[70:71]
	v_lshl_add_u64 v[134:135], v[48:49], 0, v[36:37]
	v_lshl_add_u64 v[136:137], v[50:51], 0, v[36:37]
	v_mfma_f32_16x16x32_bf16 v[78:81], v[0:3], v[178:181], 0
	v_mfma_f32_16x16x32_bf16 v[88:91], v[8:11], v[178:181], 0
	ds_read_b128 v[112:115], v73 offset:64
	ds_read_b128 v[116:119], v73 offset:4672
	ds_read_b128 v[120:123], v73 offset:2368
	ds_read_b128 v[124:127], v73 offset:6976
	v_mfma_f32_16x16x32_bf16 v[96:99], v[0:3], v[186:189], 0
	v_mfma_f32_16x16x32_bf16 v[100:103], v[4:7], v[190:193], 0
	v_mfma_f32_16x16x32_bf16 v[104:107], v[8:11], v[186:189], 0
	v_mfma_f32_16x16x32_bf16 v[108:111], v[12:15], v[190:193], 0
	s_waitcnt lgkmcnt(3)
	v_mfma_f32_16x16x32_bf16 v[52:55], v[112:115], v[194:197], v[24:27]
	s_waitcnt lgkmcnt(2)
	v_mfma_f32_16x16x32_bf16 v[48:51], v[116:119], v[198:201], v[28:31]
	s_waitcnt lgkmcnt(1)
	v_mfma_f32_16x16x32_bf16 v[20:23], v[120:123], v[194:197], v[16:19]
	s_waitcnt lgkmcnt(0)
	v_mfma_f32_16x16x32_bf16 v[16:19], v[124:127], v[198:201], v[32:35]
	v_mfma_f32_16x16x32_bf16 v[36:39], v[112:115], v[202:205], v[40:43]
	v_mfma_f32_16x16x32_bf16 v[12:15], v[120:123], v[202:205], v[56:59]
	v_mfma_f32_16x16x32_bf16 v[32:35], v[116:119], v[206:209], v[44:47]
	v_mfma_f32_16x16x32_bf16 v[8:11], v[124:127], v[206:209], v[60:63]
	v_mfma_f32_16x16x32_bf16 v[28:31], v[112:115], v[210:213], v[78:81]
	v_mfma_f32_16x16x32_bf16 v[24:27], v[116:119], v[214:217], v[84:87]
	v_mfma_f32_16x16x32_bf16 v[4:7], v[120:123], v[210:213], v[88:91]
	s_nop 1
	v_mov_b32_e32 v85, 0
	v_mov_b32_e32 v87, 0
	v_mov_b32_e32 v84, 0
	v_mfma_f32_16x16x32_bf16 v[0:3], v[124:127], v[214:217], v[92:95]
	ds_write_b32 v69, v52 offset:9216
	v_add_u32_e32 v52, s50, v67
	ds_write_b32 v52, v48
	v_mad_u32_u24 v48, v72, s67, v247
	v_add_u32_e32 v52, v48, v64
	v_lshl_add_u32 v52, v52, 2, s50
	ds_write_b32 v69, v53 offset:11280
	ds_write_b32 v52, v49
	v_mad_u32_u24 v49, v72, s67, v248
	v_add_u32_e32 v52, v49, v64
	v_lshl_add_u32 v52, v52, 2, s50
	ds_write_b32 v69, v54 offset:13344
	ds_write_b32 v52, v50
	v_mad_u32_u24 v50, v72, s67, v249
	v_add_u32_e32 v52, v50, v64
	v_lshl_add_u32 v52, v52, 2, s50
	ds_write_b32 v69, v55 offset:15408
	ds_write_b32 v52, v51
	ds_write_b32 v69, v36 offset:9280
	v_add_lshl_u32 v36, v65, v68, 2
	v_add_u32_e32 v51, s50, v36
	ds_write_b32 v51, v32
	v_add_u32_e32 v32, v48, v68
	v_add_u32_e32 v36, 0, v36
	v_lshl_add_u32 v32, v32, 2, s50
	ds_write_b32 v36, v37 offset:11280
	ds_write_b32 v32, v33
	v_add_u32_e32 v32, v49, v68
	v_lshl_add_u32 v32, v32, 2, s50
	ds_write_b32 v36, v38 offset:13344
	ds_write_b32 v32, v34
	v_add_u32_e32 v32, v50, v68
	v_lshl_add_u32 v32, v32, 2, s50
	ds_write_b32 v36, v39 offset:15408
	ds_write_b32 v32, v35
	ds_write_b32 v69, v28 offset:9344
	v_add_lshl_u32 v28, v65, v66, 2
	v_add_u32_e32 v32, s50, v28
	ds_write_b32 v32, v24
	v_add_u32_e32 v24, v48, v66
	v_add_u32_e32 v28, 0, v28
	v_lshl_add_u32 v24, v24, 2, s50
	ds_write_b32 v28, v29 offset:11280
	ds_write_b32 v24, v25
	v_add_u32_e32 v24, v49, v66
	v_lshl_add_u32 v24, v24, 2, s50
	v_mfma_f32_16x16x32_bf16 v[56:59], v[116:119], v[222:225], v[100:103]
	ds_write_b32 v28, v30 offset:13344
	ds_write_b32 v24, v26
	v_add_u32_e32 v24, v50, v66
	v_lshl_add_u32 v24, v24, 2, s50
	v_mfma_f32_16x16x32_bf16 v[60:63], v[112:115], v[218:221], v[96:99]
	ds_write_b32 v28, v31 offset:15408
	ds_write_b32 v24, v27
	v_add_lshl_u32 v24, v65, v70, 2
	v_add_u32_e32 v25, 0, v24
	v_add_u32_e32 v24, s50, v24
	ds_write_b32 v24, v56
	v_add_u32_e32 v24, v48, v70
	v_lshl_add_u32 v24, v24, 2, s50
	ds_write_b32 v25, v60 offset:9216
	ds_write_b32 v25, v61 offset:11280
	ds_write_b32 v24, v57
	v_add_u32_e32 v24, v49, v70
	v_lshl_add_u32 v24, v24, 2, s50
	ds_write_b32 v25, v62 offset:13344
	ds_write_b32 v24, v58
	v_add_u32_e32 v24, v50, v70
	v_lshl_add_u32 v24, v24, 2, s50
	ds_write_b32 v25, v63 offset:15408
	ds_write_b32 v24, v59
	v_mad_u32_u24 v24, v72, s67, v250
	v_add_u32_e32 v26, v24, v64
	ds_write_b32 v69, v20 offset:42240
	v_lshl_add_u32 v20, v26, 2, s50
	ds_write_b32 v20, v16
	v_mad_u32_u24 v16, v72, s67, v251
	v_add_u32_e32 v20, v16, v64
	v_lshl_add_u32 v20, v20, 2, s50
	ds_write_b32 v69, v21 offset:44304
	ds_write_b32 v20, v17
	v_mad_u32_u24 v17, v72, s67, v252
	v_add_u32_e32 v20, v17, v64
	v_lshl_add_u32 v20, v20, 2, s50
	ds_write_b32 v69, v22 offset:46368
	ds_write_b32 v20, v18
	v_mad_u32_u24 v18, v72, s67, v253
	v_add_u32_e32 v20, v18, v64
	v_lshl_add_u32 v20, v20, 2, s50
	ds_write_b32 v69, v23 offset:48432
	ds_write_b32 v20, v19
	v_add_u32_e32 v19, v24, v68
	ds_write_b32 v36, v12 offset:42240
	v_lshl_add_u32 v12, v19, 2, s50
	ds_write_b32 v12, v8
	v_add_u32_e32 v8, v16, v68
	v_lshl_add_u32 v8, v8, 2, s50
	ds_write_b32 v36, v13 offset:44304
	ds_write_b32 v8, v9
	v_add_u32_e32 v8, v17, v68
	v_lshl_add_u32 v8, v8, 2, s50
	ds_write_b32 v36, v14 offset:46368
	ds_write_b32 v8, v10
	v_add_u32_e32 v8, v18, v68
	v_lshl_add_u32 v8, v8, 2, s50
	ds_write_b32 v36, v15 offset:48432
	ds_write_b32 v8, v11
	v_add_u32_e32 v8, v24, v66
	ds_write_b32 v28, v4 offset:42240
	v_lshl_add_u32 v4, v8, 2, s50
	ds_write_b32 v4, v0
	v_add_u32_e32 v0, v16, v66
	v_lshl_add_u32 v0, v0, 2, s50
	ds_write_b32 v28, v5 offset:44304
	ds_write_b32 v0, v1
	v_add_u32_e32 v0, v17, v66
	v_lshl_add_u32 v0, v0, 2, s50
	v_mfma_f32_16x16x32_bf16 v[44:47], v[120:123], v[218:221], v[104:107]
	ds_write_b32 v28, v6 offset:46368
	ds_write_b32 v0, v2
	v_add_u32_e32 v0, v18, v66
	v_mfma_f32_16x16x32_bf16 v[40:43], v[124:127], v[222:225], v[108:111]
	v_lshl_add_u32 v0, v0, 2, s50
	ds_write_b32 v28, v7 offset:48432
	ds_write_b32 v0, v3
	v_add_u32_e32 v0, v24, v70
	v_lshl_add_u32 v0, v0, 2, s50
	ds_write_b32 v25, v44 offset:42240
	s_nop 1
	ds_write_b32 v0, v40
	v_add_u32_e32 v0, v16, v70
	v_lshl_add_u32 v0, v0, 2, s50
	ds_write_b32 v25, v45 offset:44304
	ds_write_b32 v0, v41
	v_add_u32_e32 v0, v17, v70
	v_lshl_add_u32 v0, v0, 2, s50
	ds_write_b32 v25, v46 offset:46368
	ds_write_b32 v0, v42
	v_add_u32_e32 v0, v18, v70
	v_lshl_add_u32 v0, v0, 2, s50
	v_lshlrev_b32_e32 v28, 5, v77
	ds_write_b32 v25, v47 offset:48432
	ds_write_b32 v0, v43
	s_waitcnt lgkmcnt(0)
	s_barrier
	global_load_dwordx4 v[20:23], v28, s[10:11] offset:16
	global_load_dwordx4 v[48:51], v28, s[10:11]
	global_load_dwordx4 v[56:59], v28, s[10:11] offset:2320
	global_load_dwordx4 v[60:63], v28, s[10:11] offset:2304
	global_load_dwordx4 v[12:15], v28, s[16:17] offset:16
	global_load_dwordx4 v[40:43], v28, s[16:17]
	global_load_dwordx4 v[24:27], v28, s[18:19] offset:16
	global_load_dwordx4 v[52:55], v28, s[18:19]
	global_load_dwordx4 v[16:19], v28, s[20:21] offset:16
	global_load_dwordx4 v[44:47], v28, s[20:21]
	global_load_dwordx4 v[4:7], v28, s[22:23] offset:16
	global_load_dwordx4 v[32:35], v28, s[22:23]
	global_load_dwordx4 v[8:11], v28, s[24:25] offset:16
	global_load_dwordx4 v[36:39], v28, s[24:25]
	global_load_dwordx4 v[0:3], v28, s[26:27] offset:16
	s_nop 0
	global_load_dwordx4 v[28:31], v28, s[26:27]
	v_subrev_u32_e32 v88, 24, v76
	v_mov_b64_e32 v[64:65], s[8:9]
	v_mad_i64_i32 v[64:65], s[4:5], v88, s62, v[64:65]
	v_lshl_add_u64 v[64:65], v[64:65], 0, v[144:145]
	v_lshl_add_u64 v[78:79], v[64:65], 0, s[88:89]
	v_add_co_u32_e32 v64, vcc, 0x1000, v64
	v_and_b32_e32 v98, 0xfff, v88
	s_nop 0
	v_addc_co_u32_e32 v65, vcc, 0, v65, vcc
	global_load_dwordx4 v[72:75], v[64:65], off offset:2048
	global_load_dwordx4 v[68:71], v[78:79], off offset:1152
	s_nop 0
	global_load_dwordx4 v[64:67], v[78:79], off offset:2176
	v_cmp_ne_u32_e32 vcc, 0, v98
	v_mov_b32_e32 v116, 0
	v_mov_b32_e32 v115, 0
	v_mov_b32_e32 v114, 0
	v_mov_b32_e32 v112, 0
	v_mov_b32_e32 v109, 0
	v_mov_b32_e32 v107, 0
	v_mov_b32_e32 v105, 0
	v_mov_b32_e32 v103, 0
	v_mov_b32_e32 v113, 0
	v_mov_b32_e32 v111, 0
	v_mov_b32_e32 v106, 0
	v_mov_b32_e32 v102, 0
	v_mov_b32_e32 v101, 0
	v_mov_b32_e32 v100, 0
	v_mov_b32_e32 v110, 0
	v_mov_b32_e32 v108, 0
	v_mov_b32_e32 v104, 0
	v_mov_b32_e32 v86, 0
	v_mov_b32_e32 v95, 0
	v_mov_b32_e32 v93, 0
	v_mov_b32_e32 v91, 0
	s_and_saveexec_b64 s[4:5], vcc
	s_cbranch_execz .LBB0_665
	v_add_co_u32_e32 v80, vcc, 0xffffc000, v78
	s_movk_i32 s0, 0xd000
	s_nop 0
	v_addc_co_u32_e32 v81, vcc, -1, v79, vcc
	v_add_co_u32_e32 v204, vcc, s0, v78
	s_nop 1
	v_addc_co_u32_e32 v205, vcc, -1, v79, vcc
	global_load_dwordx4 v[94:97], v[80:81], off offset:-512
	global_load_dwordx4 v[196:199], v[204:205], off offset:-3456
	global_load_dwordx4 v[200:203], v[204:205], off offset:-2432
	s_waitcnt vmcnt(0)
	v_lshlrev_b32_e32 v84, 16, v95
	v_and_b32_e32 v104, 0xffff0000, v95
	v_lshlrev_b32_e32 v86, 16, v96
	v_and_b32_e32 v95, 0xffff0000, v96
	v_lshlrev_b32_e32 v93, 16, v97
	v_and_b32_e32 v91, 0xffff0000, v97
	v_lshlrev_b32_e32 v110, 16, v94
	v_and_b32_e32 v108, 0xffff0000, v94
	v_lshlrev_b32_e32 v113, 16, v196
	v_and_b32_e32 v111, 0xffff0000, v196
	v_lshlrev_b32_e32 v85, 16, v197
	v_and_b32_e32 v106, 0xffff0000, v197
	v_lshlrev_b32_e32 v87, 16, v198
	v_and_b32_e32 v102, 0xffff0000, v198
	v_lshlrev_b32_e32 v101, 16, v199
	v_and_b32_e32 v100, 0xffff0000, v199
	v_lshlrev_b32_e32 v116, 16, v200
	v_and_b32_e32 v115, 0xffff0000, v200
	v_lshlrev_b32_e32 v114, 16, v201
	v_and_b32_e32 v112, 0xffff0000, v201
	v_lshlrev_b32_e32 v109, 16, v202
	v_and_b32_e32 v107, 0xffff0000, v202
	v_lshlrev_b32_e32 v105, 16, v203
	v_and_b32_e32 v103, 0xffff0000, v203
